# static s_setprio 1 for waves 4-7 also in the hyena MFMA loop (on top of v5)
# baseline (speedup 1.0000x reference)
.LBB0_500:
	s_or_b64 exec, exec, s[0:1]
	v_and_b32_e32 v0, 31, v77
	s_ashr_i32 s4, s10, 2
	v_bfe_u32 v79, v77, 4, 1
	s_and_b32 s0, s4, -16
	v_bfi_b32 v80, -16, s4, v77
	v_lshlrev_b32_e32 v0, 2, v0
	v_bfe_u32 v78, v77, 5, 1
	v_mul_u32_u24_e32 v2, 0x5a00, v79
	v_mul_lo_u32 v3, v80, s57
	v_readlane_b32 s1, v253, 46
	v_sub_u32_e32 v4, 0, v0
	s_addk_i32 s0, 0xff81
	v_add3_u32 v81, s1, v2, v3
	v_lshl_add_u32 v4, v78, 5, v4
	s_lshl_b32 s1, s0, 8
	v_lshlrev_b32_e32 v3, 4, v78
	v_subrev_u32_e32 v4, s1, v4
	s_mul_i32 s1, s0, 0xffffff70
	v_add_u32_e32 v5, 0x8000, v4
	v_add3_u32 v6, v81, v3, s1
	s_waitcnt lgkmcnt(0)
	s_barrier
	ds_read2_b32 v[38:39], v5 offset0:63 offset1:65
	ds_read2_b32 v[40:41], v5 offset0:67 offset1:69
	ds_read2_b32 v[34:35], v5 offset0:47 offset1:49
	ds_read2_b32 v[36:37], v5 offset0:51 offset1:53
	ds_read_b128 v[70:73], v6 offset:2304
	ds_read_b128 v[58:61], v6 offset:2336
	ds_read_b128 v[50:53], v6 offset:2368
	ds_read_b128 v[46:49], v6 offset:2400
	ds_read2_b32 v[42:43], v5 offset0:31 offset1:33
	ds_read2_b32 v[44:45], v5 offset0:35 offset1:37
	ds_read2_b32 v[54:55], v5 offset0:15 offset1:17
	ds_read2_b32 v[56:57], v5 offset0:19 offset1:21
	v_add_u32_e32 v6, 0x7e00, v4
	v_add_u32_e32 v4, 0x7c00, v4
	ds_read2_b32 v[62:63], v6 offset0:127 offset1:129
	ds_read2_b32 v[64:65], v5 offset0:3 offset1:5
	ds_read2_b32 v[66:67], v4 offset0:239 offset1:241
	ds_read2_b32 v[68:69], v4 offset0:243 offset1:245
	s_or_b32 s1, s4, 15
	s_cmp_lt_i32 s0, s1
	v_mov_b32_e32 v33, 0
	s_cbranch_scc0 .LBB0_503
	v_readfirstlane_b32 s5, v77
	s_cmpk_lt_u32 s5, 0x100
	s_cbranch_scc1 .Lhy_prio_skip
	s_setprio 1
.Lhy_prio_skip:
	v_lshlrev_b32_e32 v5, 5, v78
	s_lshl_b32 s4, s4, 8
	v_and_b32_e32 v4, 15, v77
	v_sub_u32_e32 v0, v5, v0
	s_and_b32 s4, s4, 0xfffff000
	v_subrev_u32_e32 v0, s4, v0
	v_mul_u32_u24_e32 v4, 0x90, v4
	v_mov_b32_e32 v18, 0
	v_add_u32_e32 v0, 0xfcbc, v0
	v_add3_u32 v82, v2, v4, v3
	v_mov_b32_e32 v19, v18
	v_mov_b32_e32 v20, v18
	v_mov_b32_e32 v21, v18
	v_mov_b32_e32 v22, v18
	v_mov_b32_e32 v23, v18
	v_mov_b32_e32 v24, v18
	v_mov_b32_e32 v25, v18
	v_mov_b32_e32 v26, v18
	v_mov_b32_e32 v27, v18
	v_mov_b32_e32 v28, v18
	v_mov_b32_e32 v29, v18
	v_mov_b32_e32 v30, v18
	v_mov_b32_e32 v31, v18
	v_mov_b32_e32 v32, v18
	v_mov_b32_e32 v33, v18
	v_mov_b32_e32 v2, v18
	v_mov_b32_e32 v3, v18
	v_mov_b32_e32 v4, v18
	v_mov_b32_e32 v5, v18
	v_mov_b32_e32 v6, v18
	v_mov_b32_e32 v7, v18
	v_mov_b32_e32 v8, v18
	v_mov_b32_e32 v9, v18
	v_mov_b32_e32 v10, v18
	v_mov_b32_e32 v11, v18
	v_mov_b32_e32 v12, v18
	v_mov_b32_e32 v13, v18
	v_mov_b32_e32 v14, v18
	v_mov_b32_e32 v15, v18
	v_mov_b32_e32 v16, v18
	v_mov_b32_e32 v17, v18

.LBB0_504:
	s_setprio 0
	s_waitcnt lgkmcnt(2)
	v_mfma_f32_32x32x16_bf16 v[18:33], v[54:57], v[70:73], v[18:33]
	s_waitcnt lgkmcnt(0)
	s_barrier
	v_mfma_f32_32x32x16_bf16 v[2:17], v[66:69], v[70:73], v[2:17]
	v_mfma_f32_32x32x16_bf16 v[18:33], v[42:45], v[58:61], v[18:33]
	v_mfma_f32_32x32x16_bf16 v[2:17], v[62:65], v[58:61], v[2:17]
	v_mfma_f32_32x32x16_bf16 v[18:33], v[34:37], v[50:53], v[18:33]
	v_mfma_f32_32x32x16_bf16 v[2:17], v[54:57], v[50:53], v[2:17]
	v_mfma_f32_32x32x16_bf16 v[18:33], v[38:41], v[46:49], v[18:33]
	v_mfma_f32_32x32x16_bf16 v[2:17], v[42:45], v[46:49], v[2:17]
	s_and_saveexec_b64 s[0:1], vcc
	v_readlane_b32 s8, v251, 35
	v_readlane_b32 s9, v251, 36
	s_movk_i32 s10, 0x5ff
	s_cbranch_execz .LBB0_472
	v_lshl_add_u32 v0, v77, 4, 0
	s_mov_b64 s[4:5], 0
